# topk list stage: per key tile a 60-comparator 16-sorter + half-cleaner + bitonic merge emitted in one piece before the next tile's loads (replaces hipcc's bitonic sorter), on top of v056
# speedup vs baseline: 1.0091x; 1.0040x over previous
.LBB0_22:
	v_or_b32_e32 v2, s44, v118
	v_mov_b32_e32 v3, v1
	v_lshlrev_b64 v[46:47], 7, v[2:3]
	v_lshl_add_u64 v[2:3], v[62:63], 0, v[46:47]
	global_load_dwordx4 v[30:33], v[2:3], off
	global_load_dwordx4 v[26:29], v[2:3], off offset:32
	global_load_dwordx4 v[22:25], v[2:3], off offset:64
	global_load_dwordx4 v[18:21], v[2:3], off offset:96
	s_nop 0
	global_load_dwordx4 v[2:5], v[66:67], off
	global_load_dwordx4 v[34:37], v[66:67], off offset:32
	global_load_dwordx4 v[38:41], v[66:67], off offset:64
	global_load_dwordx4 v[42:45], v[66:67], off offset:96
	s_waitcnt vmcnt(0)
	v_mfma_f32_32x32x16_bf16 v[2:17], v[2:5], v[30:33], 0
	s_waitcnt vmcnt(2)
	v_mfma_f32_32x32x16_bf16 v[2:17], v[34:37], v[26:29], v[2:17]
	s_waitcnt vmcnt(1)
	v_mfma_f32_32x32x16_bf16 v[2:17], v[38:41], v[22:25], v[2:17]
	s_waitcnt vmcnt(0)
	v_mfma_f32_32x32x16_bf16 v[2:17], v[42:45], v[18:21], v[2:17]
	s_nop 11
	v_and_or_b32 v2, v2, s33, v120
	v_and_or_b32 v3, v3, s33, v122
	v_and_or_b32 v4, v4, s33, v123
	v_and_or_b32 v5, v5, s33, v124
	v_and_or_b32 v6, v6, s33, v125
	v_and_or_b32 v7, v7, s33, v126
	v_and_or_b32 v8, v8, s33, v127
	v_and_or_b32 v9, v9, s33, v128
	v_and_or_b32 v10, v10, s33, v129
	v_and_or_b32 v11, v11, s33, v136
	v_and_or_b32 v12, v12, s33, v137
	v_and_or_b32 v13, v13, s33, v138
	v_and_or_b32 v14, v14, s33, v139
	v_and_or_b32 v15, v15, s33, v140
	v_and_or_b32 v16, v16, s33, v141
	v_and_or_b32 v17, v17, s33, v142
	v_max_f32_e32 v206, v2, v15
	v_min_f32_e32 v15, v2, v15
	v_max_f32_e32 v207, v3, v14
	v_min_f32_e32 v14, v3, v14
	v_max_f32_e32 v227, v4, v17
	v_min_f32_e32 v17, v4, v17
	v_max_f32_e32 v228, v5, v16
	v_min_f32_e32 v16, v5, v16
	v_max_f32_e32 v229, v6, v10
	v_min_f32_e32 v10, v6, v10
	v_max_f32_e32 v230, v7, v8
	v_min_f32_e32 v8, v7, v8
	v_max_f32_e32 v231, v9, v13
	v_min_f32_e32 v13, v9, v13
	v_max_f32_e32 v232, v11, v12
	v_min_f32_e32 v12, v11, v12
	v_max_f32_e32 v2, v206, v230
	v_min_f32_e32 v230, v206, v230
	v_max_f32_e32 v206, v207, v231
	v_min_f32_e32 v231, v207, v231
	v_max_f32_e32 v207, v227, v232
	v_min_f32_e32 v232, v227, v232
	v_max_f32_e32 v227, v228, v229
	v_min_f32_e32 v229, v228, v229
	v_max_f32_e32 v228, v8, v15
	v_min_f32_e32 v15, v8, v15
	v_max_f32_e32 v3, v10, v16
	v_min_f32_e32 v16, v10, v16
	v_max_f32_e32 v4, v12, v17
	v_min_f32_e32 v17, v12, v17
	v_max_f32_e32 v5, v13, v14
	v_min_f32_e32 v14, v13, v14
	v_max_f32_e32 v6, v2, v206
	v_min_f32_e32 v206, v2, v206
	v_max_f32_e32 v2, v207, v227
	v_min_f32_e32 v227, v207, v227
	v_max_f32_e32 v207, v229, v230
	v_min_f32_e32 v230, v229, v230
	v_max_f32_e32 v229, v228, v3
	v_min_f32_e32 v3, v228, v3
	v_max_f32_e32 v228, v231, v232
	v_min_f32_e32 v232, v231, v232
	v_max_f32_e32 v231, v4, v5
	v_min_f32_e32 v5, v4, v5
	v_max_f32_e32 v4, v14, v15
	v_min_f32_e32 v15, v14, v15
	v_max_f32_e32 v7, v16, v17
	v_min_f32_e32 v17, v16, v17
	v_max_f32_e32 v48, v6, v2
	v_min_f32_e32 v2, v6, v2
	v_max_f32_e32 v6, v206, v227
	v_min_f32_e32 v227, v206, v227
	v_max_f32_e32 v206, v207, v231
	v_min_f32_e32 v231, v207, v231
	v_max_f32_e32 v207, v230, v5
	v_min_f32_e32 v5, v230, v5
	v_max_f32_e32 v230, v229, v228
	v_min_f32_e32 v228, v229, v228
	v_max_f32_e32 v229, v3, v232
	v_min_f32_e32 v232, v3, v232
	v_max_f32_e32 v3, v4, v7
	v_min_f32_e32 v7, v4, v7
	v_min_f32_e32 v205, v15, v17
	v_max_f32_e32 v15, v15, v17
	v_max_f32_e32 v4, v6, v2
	v_min_f32_e32 v2, v6, v2
	v_max_f32_e32 v6, v227, v3
	v_min_f32_e32 v3, v227, v3
	v_max_f32_e32 v227, v206, v230
	v_min_f32_e32 v230, v206, v230
	v_max_f32_e32 v206, v207, v228
	v_min_f32_e32 v228, v207, v228
	v_max_f32_e32 v207, v229, v231
	v_min_f32_e32 v231, v229, v231
	v_max_f32_e32 v229, v232, v5
	v_min_f32_e32 v5, v232, v5
	v_max_f32_e32 v232, v15, v7
	v_min_f32_e32 v7, v15, v7
	v_max_f32_e32 v49, v4, v227
	v_min_f32_e32 v227, v4, v227
	v_max_f32_e32 v4, v2, v230
	v_min_f32_e32 v230, v2, v230
	v_max_f32_e32 v2, v206, v207
	v_min_f32_e32 v207, v206, v207
	v_max_f32_e32 v206, v228, v231
	v_min_f32_e32 v231, v228, v231
	v_max_f32_e32 v228, v229, v232
	v_min_f32_e32 v232, v229, v232
	v_min_f32_e32 v154, v5, v7
	v_max_f32_e32 v5, v5, v7
	v_max_f32_e32 v50, v4, v227
	v_min_f32_e32 v227, v4, v227
	v_max_f32_e32 v229, v6, v230
	v_min_f32_e32 v230, v6, v230
	v_max_f32_e32 v4, v228, v3
	v_min_f32_e32 v3, v228, v3
	v_min_f32_e32 v61, v5, v232
	v_max_f32_e32 v5, v5, v232
	v_max_f32_e32 v228, v229, v2
	v_min_f32_e32 v2, v229, v2
	v_max_f32_e32 v229, v230, v207
	v_min_f32_e32 v207, v230, v207
	v_max_f32_e32 v230, v206, v4
	v_min_f32_e32 v4, v206, v4
	v_max_f32_e32 v206, v231, v3
	v_min_f32_e32 v3, v231, v3
	v_max_f32_e32 v51, v228, v227
	v_min_f32_e32 v52, v228, v227
	v_max_f32_e32 v53, v2, v229
	v_min_f32_e32 v229, v2, v229
	v_max_f32_e32 v227, v230, v207
	v_min_f32_e32 v207, v230, v207
	v_min_f32_e32 v58, v4, v206
	v_max_f32_e32 v4, v4, v206
	v_max_f32_e32 v59, v5, v3
	v_min_f32_e32 v60, v5, v3
	v_max_f32_e32 v54, v229, v227
	v_min_f32_e32 v55, v229, v227
	v_max_f32_e32 v56, v207, v4
	v_min_f32_e32 v57, v207, v4
	global_load_dwordx4 v[34:37], v[68:69], off offset:96
	global_load_dwordx4 v[38:41], v[68:69], off offset:64
	global_load_dwordx4 v[42:45], v[68:69], off offset:32
	global_load_dwordx4 v[2:5], v[68:69], off
	s_waitcnt vmcnt(0)
	v_mfma_f32_32x32x16_bf16 v[2:17], v[2:5], v[30:33], 0
	v_mfma_f32_32x32x16_bf16 v[2:17], v[42:45], v[26:29], v[2:17]
	v_mfma_f32_32x32x16_bf16 v[2:17], v[38:41], v[22:25], v[2:17]
	v_mfma_f32_32x32x16_bf16 v[2:17], v[34:37], v[18:21], v[2:17]
	s_nop 11
	v_and_or_b32 v2, v2, s33, v143
	v_and_or_b32 v3, v3, s33, v144
	v_and_or_b32 v4, v4, s33, v145
	v_and_or_b32 v5, v5, s33, v146
	v_and_or_b32 v6, v6, s33, v147
	v_and_or_b32 v7, v7, s33, v148
	v_and_or_b32 v8, v8, s33, v149
	v_and_or_b32 v9, v9, s33, v150
	v_and_or_b32 v10, v10, s33, v151
	v_and_or_b32 v11, v11, s33, v152
	v_and_or_b32 v12, v12, s33, v153
	v_and_or_b32 v13, v13, s33, v160
	v_and_or_b32 v14, v14, s33, v161
	v_and_or_b32 v15, v15, s33, v162
	v_and_or_b32 v16, v16, s33, v163
	v_and_or_b32 v17, v17, s33, v164
	v_max_f32_e32 v206, v2, v15
	v_min_f32_e32 v15, v2, v15
	v_max_f32_e32 v2, v3, v14
	v_min_f32_e32 v14, v3, v14
	v_max_f32_e32 v3, v4, v17
	v_min_f32_e32 v17, v4, v17
	v_max_f32_e32 v4, v5, v16
	v_min_f32_e32 v16, v5, v16
	v_max_f32_e32 v5, v6, v10
	v_min_f32_e32 v10, v6, v10
	v_max_f32_e32 v6, v7, v8
	v_min_f32_e32 v8, v7, v8
	v_max_f32_e32 v7, v9, v13
	v_min_f32_e32 v13, v9, v13
	v_max_f32_e32 v9, v11, v12
	v_min_f32_e32 v12, v11, v12
	v_max_f32_e32 v11, v206, v6
	v_min_f32_e32 v6, v206, v6
	v_max_f32_e32 v206, v2, v7
	v_min_f32_e32 v7, v2, v7
	v_max_f32_e32 v2, v3, v9
	v_min_f32_e32 v9, v3, v9
	v_max_f32_e32 v3, v4, v5
	v_min_f32_e32 v5, v4, v5
	v_max_f32_e32 v4, v8, v15
	v_min_f32_e32 v15, v8, v15
	v_max_f32_e32 v8, v10, v16
	v_min_f32_e32 v16, v10, v16
	v_max_f32_e32 v10, v12, v17
	v_min_f32_e32 v17, v12, v17
	v_max_f32_e32 v12, v13, v14
	v_min_f32_e32 v14, v13, v14
	v_max_f32_e32 v13, v11, v206
	v_min_f32_e32 v206, v11, v206
	v_max_f32_e32 v11, v2, v3
	v_min_f32_e32 v3, v2, v3
	v_max_f32_e32 v2, v5, v6
	v_min_f32_e32 v6, v5, v6
	v_max_f32_e32 v5, v4, v8
	v_min_f32_e32 v8, v4, v8
	v_max_f32_e32 v4, v7, v9
	v_min_f32_e32 v9, v7, v9
	v_max_f32_e32 v7, v10, v12
	v_min_f32_e32 v12, v10, v12
	v_max_f32_e32 v10, v14, v15
	v_min_f32_e32 v15, v14, v15
	v_max_f32_e32 v14, v16, v17
	v_min_f32_e32 v17, v16, v17
	v_max_f32_e32 v16, v13, v11
	v_min_f32_e32 v11, v13, v11
	v_max_f32_e32 v13, v206, v3
	v_min_f32_e32 v3, v206, v3
	v_max_f32_e32 v206, v2, v7
	v_min_f32_e32 v7, v2, v7
	v_max_f32_e32 v2, v6, v12
	v_min_f32_e32 v12, v6, v12
	v_max_f32_e32 v6, v5, v4
	v_min_f32_e32 v4, v5, v4
	v_max_f32_e32 v5, v8, v9
	v_min_f32_e32 v9, v8, v9
	v_max_f32_e32 v8, v10, v14
	v_min_f32_e32 v14, v10, v14
	v_max_f32_e32 v10, v15, v17
	v_min_f32_e32 v17, v15, v17
	v_max_f32_e32 v15, v13, v11
	v_min_f32_e32 v11, v13, v11
	v_max_f32_e32 v13, v3, v8
	v_min_f32_e32 v8, v3, v8
	v_max_f32_e32 v3, v206, v6
	v_min_f32_e32 v6, v206, v6
	v_max_f32_e32 v206, v2, v4
	v_min_f32_e32 v4, v2, v4
	v_max_f32_e32 v2, v5, v7
	v_min_f32_e32 v7, v5, v7
	v_max_f32_e32 v5, v9, v12
	v_min_f32_e32 v12, v9, v12
	v_max_f32_e32 v9, v10, v14
	v_min_f32_e32 v14, v10, v14
	v_max_f32_e32 v10, v15, v3
	v_min_f32_e32 v3, v15, v3
	v_max_f32_e32 v15, v11, v6
	v_min_f32_e32 v6, v11, v6
	v_max_f32_e32 v11, v206, v2
	v_min_f32_e32 v2, v206, v2
	v_max_f32_e32 v206, v4, v7
	v_min_f32_e32 v7, v4, v7
	v_max_f32_e32 v4, v5, v9
	v_min_f32_e32 v9, v5, v9
	v_max_f32_e32 v5, v12, v14
	v_min_f32_e32 v14, v12, v14
	v_max_f32_e32 v12, v15, v3
	v_min_f32_e32 v3, v15, v3
	v_max_f32_e32 v15, v13, v6
	v_min_f32_e32 v6, v13, v6
	v_max_f32_e32 v13, v4, v8
	v_min_f32_e32 v8, v4, v8
	v_max_f32_e32 v4, v5, v9
	v_min_f32_e32 v9, v5, v9
	v_max_f32_e32 v5, v15, v11
	v_min_f32_e32 v11, v15, v11
	v_max_f32_e32 v15, v6, v2
	v_min_f32_e32 v2, v6, v2
	v_max_f32_e32 v6, v206, v13
	v_min_f32_e32 v13, v206, v13
	v_max_f32_e32 v206, v7, v8
	v_min_f32_e32 v8, v7, v8
	v_max_f32_e32 v7, v5, v3
	v_min_f32_e32 v3, v5, v3
	v_max_f32_e32 v5, v11, v15
	v_min_f32_e32 v15, v11, v15
	v_max_f32_e32 v11, v6, v2
	v_min_f32_e32 v2, v6, v2
	v_max_f32_e32 v6, v13, v206
	v_min_f32_e32 v206, v13, v206
	v_max_f32_e32 v13, v4, v8
	v_min_f32_e32 v8, v4, v8
	v_max_f32_e32 v4, v15, v11
	v_min_f32_e32 v11, v15, v11
	v_max_f32_e32 v15, v2, v6
	v_min_f32_e32 v6, v2, v6
	v_max_f32_e32 v17, v48, v17
	v_max_f32_e32 v14, v49, v14
	v_max_f32_e32 v9, v50, v9
	v_max_f32_e32 v8, v51, v8
	v_max_f32_e32 v13, v52, v13
	v_max_f32_e32 v206, v53, v206
	v_max_f32_e32 v6, v54, v6
	v_max_f32_e32 v15, v55, v15
	v_max_f32_e32 v11, v56, v11
	v_max_f32_e32 v4, v57, v4
	v_max_f32_e32 v5, v58, v5
	v_max_f32_e32 v3, v59, v3
	v_max_f32_e32 v7, v60, v7
	v_max_f32_e32 v12, v61, v12
	v_max_f32_e32 v10, v154, v10
	v_max_f32_e32 v16, v205, v16
	v_max_f32_e32 v2, v16, v15
	v_min_f32_e32 v15, v16, v15
	v_max_f32_e32 v16, v10, v6
	v_min_f32_e32 v6, v10, v6
	v_max_f32_e32 v10, v12, v206
	v_min_f32_e32 v206, v12, v206
	v_max_f32_e32 v12, v7, v13
	v_min_f32_e32 v13, v7, v13
	v_max_f32_e32 v7, v3, v8
	v_min_f32_e32 v8, v3, v8
	v_max_f32_e32 v3, v5, v9
	v_min_f32_e32 v9, v5, v9
	v_max_f32_e32 v5, v4, v14
	v_min_f32_e32 v14, v4, v14
	v_max_f32_e32 v4, v11, v17
	v_min_f32_e32 v17, v11, v17
	v_max_f32_e32 v11, v2, v7
	v_min_f32_e32 v7, v2, v7
	v_max_f32_e32 v2, v16, v3
	v_min_f32_e32 v3, v16, v3
	v_max_f32_e32 v16, v10, v5
	v_min_f32_e32 v5, v10, v5
	v_max_f32_e32 v10, v12, v4
	v_min_f32_e32 v4, v12, v4
	v_max_f32_e32 v12, v15, v8
	v_min_f32_e32 v8, v15, v8
	v_max_f32_e32 v15, v6, v9
	v_min_f32_e32 v9, v6, v9
	v_max_f32_e32 v6, v206, v14
	v_min_f32_e32 v14, v206, v14
	v_max_f32_e32 v48, v13, v17
	v_min_f32_e32 v17, v13, v17
	v_max_f32_e32 v13, v11, v16
	v_min_f32_e32 v16, v11, v16
	v_max_f32_e32 v11, v2, v10
	v_min_f32_e32 v10, v2, v10
	v_max_f32_e32 v2, v7, v5
	v_min_f32_e32 v5, v7, v5
	v_max_f32_e32 v7, v3, v4
	v_min_f32_e32 v4, v3, v4
	v_max_f32_e32 v3, v12, v6
	v_min_f32_e32 v6, v12, v6
	v_max_f32_e32 v12, v15, v48
	v_min_f32_e32 v48, v15, v48
	v_max_f32_e32 v15, v8, v14
	v_min_f32_e32 v14, v8, v14
	v_max_f32_e32 v8, v9, v17
	v_min_f32_e32 v17, v9, v17
	v_max_f32_e32 v206, v13, v11
	v_min_f32_e32 v207, v13, v11
	v_max_f32_e32 v227, v16, v10
	v_min_f32_e32 v228, v16, v10
	v_max_f32_e32 v229, v2, v7
	v_min_f32_e32 v230, v2, v7
	v_max_f32_e32 v231, v5, v4
	v_min_f32_e32 v232, v5, v4
	v_max_f32_e32 v233, v3, v12
	v_min_f32_e32 v234, v3, v12
	v_max_f32_e32 v235, v6, v48
	v_min_f32_e32 v48, v6, v48
	v_max_f32_e32 v49, v15, v8
	v_min_f32_e32 v50, v15, v8
	v_max_f32_e32 v51, v14, v17
	v_min_f32_e32 v52, v14, v17
	global_load_dwordx4 v[34:37], v[70:71], off offset:96
	global_load_dwordx4 v[38:41], v[70:71], off offset:64
	global_load_dwordx4 v[42:45], v[70:71], off offset:32
	global_load_dwordx4 v[2:5], v[70:71], off
	s_waitcnt vmcnt(0)
	v_mfma_f32_32x32x16_bf16 v[2:17], v[2:5], v[30:33], 0
	v_mfma_f32_32x32x16_bf16 v[2:17], v[42:45], v[26:29], v[2:17]
	v_mfma_f32_32x32x16_bf16 v[2:17], v[38:41], v[22:25], v[2:17]
	v_mfma_f32_32x32x16_bf16 v[2:17], v[34:37], v[18:21], v[2:17]
	s_nop 11
	v_and_or_b32 v2, v2, s33, v165
	v_and_or_b32 v3, v3, s33, v166
	v_and_or_b32 v4, v4, s33, v167
	v_and_or_b32 v5, v5, s33, v168
	v_and_or_b32 v6, v6, s33, v169
	v_and_or_b32 v7, v7, s33, v170
	v_and_or_b32 v8, v8, s33, v171
	v_and_or_b32 v9, v9, s33, v172
	v_and_or_b32 v10, v10, s33, v173
	v_and_or_b32 v11, v11, s33, v174
	v_and_or_b32 v12, v12, s33, v175
	v_and_or_b32 v13, v13, s33, v184
	v_and_or_b32 v14, v14, s33, v185
	v_and_or_b32 v15, v15, s33, v186
	v_and_or_b32 v16, v16, s33, v187
	v_and_or_b32 v17, v17, s33, v188
	v_max_f32_e32 v53, v2, v15
	v_min_f32_e32 v15, v2, v15
	v_max_f32_e32 v2, v3, v14
	v_min_f32_e32 v14, v3, v14
	v_max_f32_e32 v3, v4, v17
	v_min_f32_e32 v17, v4, v17
	v_max_f32_e32 v4, v5, v16
	v_min_f32_e32 v16, v5, v16
	v_max_f32_e32 v5, v6, v10
	v_min_f32_e32 v10, v6, v10
	v_max_f32_e32 v6, v7, v8
	v_min_f32_e32 v8, v7, v8
	v_max_f32_e32 v7, v9, v13
	v_min_f32_e32 v13, v9, v13
	v_max_f32_e32 v9, v11, v12
	v_min_f32_e32 v12, v11, v12
	v_max_f32_e32 v11, v53, v6
	v_min_f32_e32 v6, v53, v6
	v_max_f32_e32 v53, v2, v7
	v_min_f32_e32 v7, v2, v7
	v_max_f32_e32 v2, v3, v9
	v_min_f32_e32 v9, v3, v9
	v_max_f32_e32 v3, v4, v5
	v_min_f32_e32 v5, v4, v5
	v_max_f32_e32 v4, v8, v15
	v_min_f32_e32 v15, v8, v15
	v_max_f32_e32 v8, v10, v16
	v_min_f32_e32 v16, v10, v16
	v_max_f32_e32 v10, v12, v17
	v_min_f32_e32 v17, v12, v17
	v_max_f32_e32 v12, v13, v14
	v_min_f32_e32 v14, v13, v14
	v_max_f32_e32 v13, v11, v53
	v_min_f32_e32 v53, v11, v53
	v_max_f32_e32 v11, v2, v3
	v_min_f32_e32 v3, v2, v3
	v_max_f32_e32 v2, v5, v6
	v_min_f32_e32 v6, v5, v6
	v_max_f32_e32 v5, v4, v8
	v_min_f32_e32 v8, v4, v8
	v_max_f32_e32 v4, v7, v9
	v_min_f32_e32 v9, v7, v9
	v_max_f32_e32 v7, v10, v12
	v_min_f32_e32 v12, v10, v12
	v_max_f32_e32 v10, v14, v15
	v_min_f32_e32 v15, v14, v15
	v_max_f32_e32 v14, v16, v17
	v_min_f32_e32 v17, v16, v17
	v_max_f32_e32 v16, v13, v11
	v_min_f32_e32 v11, v13, v11
	v_max_f32_e32 v13, v53, v3
	v_min_f32_e32 v3, v53, v3
	v_max_f32_e32 v53, v2, v7
	v_min_f32_e32 v7, v2, v7
	v_max_f32_e32 v2, v6, v12
	v_min_f32_e32 v12, v6, v12
	v_max_f32_e32 v6, v5, v4
	v_min_f32_e32 v4, v5, v4
	v_max_f32_e32 v5, v8, v9
	v_min_f32_e32 v9, v8, v9
	v_max_f32_e32 v8, v10, v14
	v_min_f32_e32 v14, v10, v14
	v_max_f32_e32 v10, v15, v17
	v_min_f32_e32 v17, v15, v17
	v_max_f32_e32 v15, v13, v11
	v_min_f32_e32 v11, v13, v11
	v_max_f32_e32 v13, v3, v8
	v_min_f32_e32 v8, v3, v8
	v_max_f32_e32 v3, v53, v6
	v_min_f32_e32 v6, v53, v6
	v_max_f32_e32 v53, v2, v4
	v_min_f32_e32 v4, v2, v4
	v_max_f32_e32 v2, v5, v7
	v_min_f32_e32 v7, v5, v7
	v_max_f32_e32 v5, v9, v12
	v_min_f32_e32 v12, v9, v12
	v_max_f32_e32 v9, v10, v14
	v_min_f32_e32 v14, v10, v14
	v_max_f32_e32 v10, v15, v3
	v_min_f32_e32 v3, v15, v3
	v_max_f32_e32 v15, v11, v6
	v_min_f32_e32 v6, v11, v6
	v_max_f32_e32 v11, v53, v2
	v_min_f32_e32 v2, v53, v2
	v_max_f32_e32 v53, v4, v7
	v_min_f32_e32 v7, v4, v7
	v_max_f32_e32 v4, v5, v9
	v_min_f32_e32 v9, v5, v9
	v_max_f32_e32 v5, v12, v14
	v_min_f32_e32 v14, v12, v14
	v_max_f32_e32 v12, v15, v3
	v_min_f32_e32 v3, v15, v3
	v_max_f32_e32 v15, v13, v6
	v_min_f32_e32 v6, v13, v6
	v_max_f32_e32 v13, v4, v8
	v_min_f32_e32 v8, v4, v8
	v_max_f32_e32 v4, v5, v9
	v_min_f32_e32 v9, v5, v9
	v_max_f32_e32 v5, v15, v11
	v_min_f32_e32 v11, v15, v11
	v_max_f32_e32 v15, v6, v2
	v_min_f32_e32 v2, v6, v2
	v_max_f32_e32 v6, v53, v13
	v_min_f32_e32 v13, v53, v13
	v_max_f32_e32 v53, v7, v8
	v_min_f32_e32 v8, v7, v8
	v_max_f32_e32 v7, v5, v3
	v_min_f32_e32 v3, v5, v3
	v_max_f32_e32 v5, v11, v15
	v_min_f32_e32 v15, v11, v15
	v_max_f32_e32 v11, v6, v2
	v_min_f32_e32 v2, v6, v2
	v_max_f32_e32 v6, v13, v53
	v_min_f32_e32 v53, v13, v53
	v_max_f32_e32 v13, v4, v8
	v_min_f32_e32 v8, v4, v8
	v_max_f32_e32 v4, v15, v11
	v_min_f32_e32 v11, v15, v11
	v_max_f32_e32 v15, v2, v6
	v_min_f32_e32 v6, v2, v6
	v_max_f32_e32 v17, v206, v17
	v_max_f32_e32 v14, v207, v14
	v_max_f32_e32 v9, v227, v9
	v_max_f32_e32 v8, v228, v8
	v_max_f32_e32 v13, v229, v13
	v_max_f32_e32 v53, v230, v53
	v_max_f32_e32 v6, v231, v6
	v_max_f32_e32 v15, v232, v15
	v_max_f32_e32 v11, v233, v11
	v_max_f32_e32 v4, v234, v4
	v_max_f32_e32 v5, v235, v5
	v_max_f32_e32 v3, v48, v3
	v_max_f32_e32 v7, v49, v7
	v_max_f32_e32 v12, v50, v12
	v_max_f32_e32 v10, v51, v10
	v_max_f32_e32 v16, v52, v16
	v_max_f32_e32 v2, v16, v15
	v_min_f32_e32 v15, v16, v15
	v_max_f32_e32 v16, v10, v6
	v_min_f32_e32 v6, v10, v6
	v_max_f32_e32 v10, v12, v53
	v_min_f32_e32 v53, v12, v53
	v_max_f32_e32 v12, v7, v13
	v_min_f32_e32 v13, v7, v13
	v_max_f32_e32 v7, v3, v8
	v_min_f32_e32 v8, v3, v8
	v_max_f32_e32 v3, v5, v9
	v_min_f32_e32 v9, v5, v9
	v_max_f32_e32 v5, v4, v14
	v_min_f32_e32 v14, v4, v14
	v_max_f32_e32 v4, v11, v17
	v_min_f32_e32 v17, v11, v17
	v_max_f32_e32 v11, v2, v7
	v_min_f32_e32 v7, v2, v7
	v_max_f32_e32 v2, v16, v3
	v_min_f32_e32 v3, v16, v3
	v_max_f32_e32 v16, v10, v5
	v_min_f32_e32 v5, v10, v5
	v_max_f32_e32 v10, v12, v4
	v_min_f32_e32 v4, v12, v4
	v_max_f32_e32 v12, v15, v8
	v_min_f32_e32 v8, v15, v8
	v_max_f32_e32 v15, v6, v9
	v_min_f32_e32 v9, v6, v9
	v_max_f32_e32 v6, v53, v14
	v_min_f32_e32 v14, v53, v14
	v_max_f32_e32 v206, v13, v17
	v_min_f32_e32 v17, v13, v17
	v_max_f32_e32 v13, v11, v16
	v_min_f32_e32 v16, v11, v16
	v_max_f32_e32 v11, v2, v10
	v_min_f32_e32 v10, v2, v10
	v_max_f32_e32 v2, v7, v5
	v_min_f32_e32 v5, v7, v5
	v_max_f32_e32 v7, v3, v4
	v_min_f32_e32 v4, v3, v4
	v_max_f32_e32 v3, v12, v6
	v_min_f32_e32 v6, v12, v6
	v_max_f32_e32 v12, v15, v206
	v_min_f32_e32 v206, v15, v206
	v_max_f32_e32 v15, v8, v14
	v_min_f32_e32 v14, v8, v14
	v_max_f32_e32 v8, v9, v17
	v_min_f32_e32 v17, v9, v17
	v_max_f32_e32 v53, v13, v11
	v_min_f32_e32 v54, v13, v11
	v_max_f32_e32 v55, v16, v10
	v_min_f32_e32 v56, v16, v10
	v_max_f32_e32 v57, v2, v7
	v_min_f32_e32 v58, v2, v7
	v_max_f32_e32 v59, v5, v4
	v_min_f32_e32 v60, v5, v4
	v_max_f32_e32 v61, v3, v12
	v_min_f32_e32 v154, v3, v12
	v_max_f32_e32 v205, v6, v206
	v_min_f32_e32 v48, v6, v206
	v_max_f32_e32 v49, v15, v8
	v_min_f32_e32 v50, v15, v8
	v_max_f32_e32 v51, v14, v17
	v_min_f32_e32 v52, v14, v17
	global_load_dwordx4 v[34:37], v[72:73], off offset:96
	global_load_dwordx4 v[38:41], v[72:73], off offset:64
	global_load_dwordx4 v[42:45], v[72:73], off offset:32
	global_load_dwordx4 v[2:5], v[72:73], off
	s_waitcnt vmcnt(0)
	v_mfma_f32_32x32x16_bf16 v[2:17], v[2:5], v[30:33], 0
	v_mfma_f32_32x32x16_bf16 v[2:17], v[42:45], v[26:29], v[2:17]
	v_mfma_f32_32x32x16_bf16 v[2:17], v[38:41], v[22:25], v[2:17]
	v_mfma_f32_32x32x16_bf16 v[2:17], v[34:37], v[18:21], v[2:17]
	s_nop 11
	v_and_or_b32 v2, v2, s33, v189
	v_and_or_b32 v3, v3, s33, v190
	v_and_or_b32 v4, v4, s33, v191
	v_and_or_b32 v5, v5, s33, v192
	v_and_or_b32 v6, v6, s33, v193
	v_and_or_b32 v7, v7, s33, v194
	v_and_or_b32 v8, v8, s33, v195
	v_and_or_b32 v9, v9, s33, v196
	v_and_or_b32 v10, v10, s33, v197
	v_and_or_b32 v11, v11, s33, v198
	v_and_or_b32 v12, v12, s33, v199
	v_and_or_b32 v13, v13, s33, v200
	v_and_or_b32 v14, v14, s33, v201
	v_and_or_b32 v15, v15, s33, v202
	v_and_or_b32 v16, v16, s33, v203
	v_and_or_b32 v17, v17, s33, v204
	v_max_f32_e32 v19, v2, v15
	v_min_f32_e32 v15, v2, v15
	v_max_f32_e32 v20, v3, v14
	v_min_f32_e32 v14, v3, v14
	v_max_f32_e32 v21, v4, v17
	v_min_f32_e32 v17, v4, v17
	v_max_f32_e32 v22, v5, v16
	v_min_f32_e32 v16, v5, v16
	v_max_f32_e32 v23, v6, v10
	v_min_f32_e32 v10, v6, v10
	v_max_f32_e32 v24, v7, v8
	v_min_f32_e32 v8, v7, v8
	v_max_f32_e32 v25, v9, v13
	v_min_f32_e32 v13, v9, v13
	v_max_f32_e32 v26, v11, v12
	v_min_f32_e32 v12, v11, v12
	v_max_f32_e32 v27, v19, v24
	v_min_f32_e32 v24, v19, v24
	v_max_f32_e32 v19, v20, v25
	v_min_f32_e32 v25, v20, v25
	v_max_f32_e32 v20, v21, v26
	v_min_f32_e32 v26, v21, v26
	v_max_f32_e32 v21, v22, v23
	v_min_f32_e32 v23, v22, v23
	v_max_f32_e32 v22, v8, v15
	v_min_f32_e32 v15, v8, v15
	v_max_f32_e32 v28, v10, v16
	v_min_f32_e32 v16, v10, v16
	v_max_f32_e32 v29, v12, v17
	v_min_f32_e32 v17, v12, v17
	v_max_f32_e32 v30, v13, v14
	v_min_f32_e32 v14, v13, v14
	v_max_f32_e32 v31, v27, v19
	v_min_f32_e32 v19, v27, v19
	v_max_f32_e32 v27, v20, v21
	v_min_f32_e32 v21, v20, v21
	v_max_f32_e32 v20, v23, v24
	v_min_f32_e32 v24, v23, v24
	v_max_f32_e32 v23, v22, v28
	v_min_f32_e32 v28, v22, v28
	v_max_f32_e32 v22, v25, v26
	v_min_f32_e32 v26, v25, v26
	v_max_f32_e32 v25, v29, v30
	v_min_f32_e32 v30, v29, v30
	v_max_f32_e32 v29, v14, v15
	v_min_f32_e32 v15, v14, v15
	v_max_f32_e32 v32, v16, v17
	v_min_f32_e32 v17, v16, v17
	v_max_f32_e32 v2, v31, v27
	v_min_f32_e32 v27, v31, v27
	v_max_f32_e32 v31, v19, v21
	v_min_f32_e32 v21, v19, v21
	v_max_f32_e32 v19, v20, v25
	v_min_f32_e32 v25, v20, v25
	v_max_f32_e32 v20, v24, v30
	v_min_f32_e32 v30, v24, v30
	v_max_f32_e32 v24, v23, v22
	v_min_f32_e32 v22, v23, v22
	v_max_f32_e32 v23, v28, v26
	v_min_f32_e32 v26, v28, v26
	v_max_f32_e32 v28, v29, v32
	v_min_f32_e32 v32, v29, v32
	v_max_f32_e32 v29, v15, v17
	v_min_f32_e32 v17, v15, v17
	v_max_f32_e32 v3, v31, v27
	v_min_f32_e32 v27, v31, v27
	v_max_f32_e32 v31, v21, v28
	v_min_f32_e32 v28, v21, v28
	v_max_f32_e32 v21, v19, v24
	v_min_f32_e32 v24, v19, v24
	v_max_f32_e32 v19, v20, v22
	v_min_f32_e32 v22, v20, v22
	v_max_f32_e32 v20, v23, v25
	v_min_f32_e32 v25, v23, v25
	v_max_f32_e32 v23, v26, v30
	v_min_f32_e32 v30, v26, v30
	v_max_f32_e32 v26, v29, v32
	v_min_f32_e32 v32, v29, v32
	v_max_f32_e32 v29, v3, v21
	v_min_f32_e32 v21, v3, v21
	v_max_f32_e32 v3, v27, v24
	v_min_f32_e32 v24, v27, v24
	v_max_f32_e32 v27, v19, v20
	v_min_f32_e32 v20, v19, v20
	v_max_f32_e32 v19, v22, v25
	v_min_f32_e32 v25, v22, v25
	v_max_f32_e32 v22, v23, v26
	v_min_f32_e32 v26, v23, v26
	v_max_f32_e32 v23, v30, v32
	v_min_f32_e32 v32, v30, v32
	v_max_f32_e32 v30, v3, v21
	v_min_f32_e32 v21, v3, v21
	v_max_f32_e32 v3, v31, v24
	v_min_f32_e32 v24, v31, v24
	v_max_f32_e32 v31, v22, v28
	v_min_f32_e32 v28, v22, v28
	v_max_f32_e32 v22, v23, v26
	v_min_f32_e32 v26, v23, v26
	v_max_f32_e32 v23, v3, v27
	v_min_f32_e32 v27, v3, v27
	v_max_f32_e32 v3, v24, v20
	v_min_f32_e32 v20, v24, v20
	v_max_f32_e32 v24, v19, v31
	v_min_f32_e32 v31, v19, v31
	v_max_f32_e32 v19, v25, v28
	v_min_f32_e32 v28, v25, v28
	v_max_f32_e32 v25, v23, v21
	v_min_f32_e32 v21, v23, v21
	v_max_f32_e32 v23, v27, v3
	v_min_f32_e32 v3, v27, v3
	v_max_f32_e32 v27, v24, v20
	v_min_f32_e32 v20, v24, v20
	v_max_f32_e32 v24, v31, v19
	v_min_f32_e32 v19, v31, v19
	v_max_f32_e32 v31, v22, v28
	v_min_f32_e32 v28, v22, v28
	v_max_f32_e32 v22, v3, v27
	v_min_f32_e32 v27, v3, v27
	v_max_f32_e32 v3, v20, v24
	v_min_f32_e32 v24, v20, v24
	v_max_f32_e32 v17, v53, v17
	v_max_f32_e32 v32, v54, v32
	v_max_f32_e32 v26, v55, v26
	v_max_f32_e32 v28, v56, v28
	v_max_f32_e32 v31, v57, v31
	v_max_f32_e32 v19, v58, v19
	v_max_f32_e32 v24, v59, v24
	v_max_f32_e32 v3, v60, v3
	v_max_f32_e32 v27, v61, v27
	v_max_f32_e32 v22, v154, v22
	v_max_f32_e32 v23, v205, v23
	v_max_f32_e32 v21, v48, v21
	v_max_f32_e32 v25, v49, v25
	v_max_f32_e32 v30, v50, v30
	v_max_f32_e32 v29, v51, v29
	v_max_f32_e32 v2, v52, v2
	v_max_f32_e32 v20, v2, v3
	v_min_f32_e32 v3, v2, v3
	v_max_f32_e32 v2, v29, v24
	v_min_f32_e32 v24, v29, v24
	v_max_f32_e32 v29, v30, v19
	v_min_f32_e32 v19, v30, v19
	v_max_f32_e32 v30, v25, v31
	v_min_f32_e32 v31, v25, v31
	v_max_f32_e32 v25, v21, v28
	v_min_f32_e32 v28, v21, v28
	v_max_f32_e32 v21, v23, v26
	v_min_f32_e32 v26, v23, v26
	v_max_f32_e32 v23, v22, v32
	v_min_f32_e32 v32, v22, v32
	v_max_f32_e32 v22, v27, v17
	v_min_f32_e32 v17, v27, v17
	v_max_f32_e32 v27, v20, v25
	v_min_f32_e32 v25, v20, v25
	v_max_f32_e32 v20, v2, v21
	v_min_f32_e32 v21, v2, v21
	v_max_f32_e32 v2, v29, v23
	v_min_f32_e32 v23, v29, v23
	v_max_f32_e32 v29, v30, v22
	v_min_f32_e32 v22, v30, v22
	v_max_f32_e32 v30, v3, v28
	v_min_f32_e32 v28, v3, v28
	v_max_f32_e32 v3, v24, v26
	v_min_f32_e32 v26, v24, v26
	v_max_f32_e32 v24, v19, v32
	v_min_f32_e32 v32, v19, v32
	v_max_f32_e32 v19, v31, v17
	v_min_f32_e32 v17, v31, v17
	v_max_f32_e32 v31, v27, v2
	v_min_f32_e32 v2, v27, v2
	v_max_f32_e32 v27, v20, v29
	v_min_f32_e32 v29, v20, v29
	v_max_f32_e32 v20, v25, v23
	v_min_f32_e32 v23, v25, v23
	v_max_f32_e32 v25, v21, v22
	v_min_f32_e32 v22, v21, v22
	v_max_f32_e32 v21, v30, v24
	v_min_f32_e32 v24, v30, v24
	v_max_f32_e32 v30, v3, v19
	v_min_f32_e32 v19, v3, v19
	v_max_f32_e32 v3, v28, v32
	v_min_f32_e32 v32, v28, v32
	v_max_f32_e32 v28, v26, v17
	v_min_f32_e32 v17, v26, v17
	v_max_f32_e32 v15, v31, v27
	v_min_f32_e32 v27, v31, v27
	v_max_f32_e32 v12, v2, v29
	v_min_f32_e32 v5, v2, v29
	v_max_f32_e32 v9, v20, v25
	v_min_f32_e32 v25, v20, v25
	v_max_f32_e32 v18, v23, v22
	v_min_f32_e32 v4, v23, v22
	v_max_f32_e32 v11, v21, v30
	v_min_f32_e32 v13, v21, v30
	v_max_f32_e32 v16, v24, v19
	v_min_f32_e32 v7, v24, v19
	v_max_f32_e32 v14, v3, v28
	v_min_f32_e32 v8, v3, v28
	v_max_f32_e32 v10, v32, v17
	v_min_f32_e32 v2, v32, v17
	v_mov_b32_e32 v3, v27
	v_mov_b32_e32 v17, v25
	ds_bpermute_b32 v6, v121, v15
	ds_bpermute_b32 v19, v121, v3
	ds_bpermute_b32 v20, v121, v12
	ds_bpermute_b32 v21, v121, v5
	ds_bpermute_b32 v22, v121, v9
	ds_bpermute_b32 v23, v121, v17
	ds_bpermute_b32 v24, v121, v18
	ds_bpermute_b32 v25, v121, v4
	ds_bpermute_b32 v26, v121, v11
	ds_bpermute_b32 v27, v121, v13
	ds_bpermute_b32 v28, v121, v16
	ds_bpermute_b32 v29, v121, v7
	ds_bpermute_b32 v30, v121, v14
	ds_bpermute_b32 v31, v121, v8
	ds_bpermute_b32 v32, v121, v10
	ds_bpermute_b32 v33, v121, v2
	s_waitcnt lgkmcnt(4)
	s_waitcnt lgkmcnt(3)
	s_waitcnt lgkmcnt(2)
	s_waitcnt lgkmcnt(1)
	s_waitcnt lgkmcnt(0)
	v_max_f32_e32 v15, v15, v33
	v_max_f32_e32 v3, v3, v32
	v_max_f32_e32 v12, v12, v31
	v_max_f32_e32 v5, v5, v30
	v_max_f32_e32 v9, v9, v29
	v_max_f32_e32 v17, v17, v28
	v_max_f32_e32 v18, v18, v27
	v_max_f32_e32 v4, v4, v26
	v_max_f32_e32 v11, v11, v25
	v_max_f32_e32 v13, v13, v24
	v_max_f32_e32 v16, v16, v23
	v_max_f32_e32 v7, v7, v22
	v_max_f32_e32 v14, v14, v21
	v_max_f32_e32 v8, v8, v20
	v_max_f32_e32 v10, v10, v19
	v_max_f32_e32 v2, v2, v6
	v_max_f32_e32 v6, v15, v11
	v_min_f32_e32 v11, v15, v11
	v_max_f32_e32 v15, v3, v13
	v_min_f32_e32 v3, v3, v13
	v_max_f32_e32 v13, v12, v16
	v_min_f32_e32 v12, v12, v16
	v_max_f32_e32 v16, v5, v7
	v_min_f32_e32 v5, v5, v7
	v_max_f32_e32 v7, v9, v14
	v_min_f32_e32 v9, v9, v14
	v_max_f32_e32 v14, v17, v8
	v_min_f32_e32 v8, v17, v8
	v_max_f32_e32 v17, v18, v10
	v_min_f32_e32 v10, v18, v10
	v_max_f32_e32 v18, v4, v2
	v_min_f32_e32 v2, v4, v2
	v_max_f32_e32 v4, v6, v7
	v_min_f32_e32 v6, v6, v7
	v_max_f32_e32 v7, v15, v14
	v_min_f32_e32 v14, v15, v14
	v_max_f32_e32 v15, v13, v17
	v_min_f32_e32 v13, v13, v17
	v_max_f32_e32 v17, v16, v18
	v_min_f32_e32 v16, v16, v18
	v_max_f32_e32 v18, v11, v9
	v_min_f32_e32 v9, v11, v9
	v_max_f32_e32 v11, v3, v8
	v_min_f32_e32 v3, v3, v8
	v_max_f32_e32 v8, v12, v10
	v_min_f32_e32 v10, v12, v10
	v_max_f32_e32 v12, v5, v2
	v_min_f32_e32 v2, v5, v2
	v_max_f32_e32 v5, v4, v15
	v_min_f32_e32 v4, v4, v15
	v_max_f32_e32 v15, v7, v17
	v_min_f32_e32 v7, v7, v17
	v_max_f32_e32 v17, v6, v13
	v_min_f32_e32 v6, v6, v13
	v_max_f32_e32 v13, v14, v16
	v_min_f32_e32 v14, v14, v16
	v_max_f32_e32 v16, v18, v8
	v_min_f32_e32 v8, v18, v8
	v_max_f32_e32 v18, v11, v12
	v_min_f32_e32 v11, v11, v12
	v_max_f32_e32 v12, v9, v10
	v_min_f32_e32 v9, v9, v10
	v_max_f32_e32 v10, v3, v2
	v_min_f32_e32 v2, v3, v2
	v_max_f32_e32 v20, v9, v2
	v_min_f32_e32 v21, v9, v2
	v_lshl_add_u64 v[2:3], v[64:65], 0, v[46:47]
	v_max_f32_e32 v30, v5, v15
	v_min_f32_e32 v31, v5, v15
	v_max_f32_e32 v32, v4, v7
	v_min_f32_e32 v33, v4, v7
	global_load_dwordx4 v[46:49], v[2:3], off
	global_load_dwordx4 v[42:45], v[2:3], off offset:32
	global_load_dwordx4 v[38:41], v[2:3], off offset:64
	global_load_dwordx4 v[34:37], v[2:3], off offset:96
	s_nop 0
	global_load_dwordx4 v[2:5], v[90:91], off
	global_load_dwordx4 v[58:61], v[90:91], off offset:32
	global_load_dwordx4 v[54:57], v[90:91], off offset:64
	global_load_dwordx4 v[50:53], v[90:91], off offset:96
	v_max_f32_e32 v26, v17, v13
	v_min_f32_e32 v27, v17, v13
	v_max_f32_e32 v28, v6, v14
	v_min_f32_e32 v29, v6, v14
	v_max_f32_e32 v22, v16, v18
	v_min_f32_e32 v23, v16, v18
	v_max_f32_e32 v24, v8, v11
	v_min_f32_e32 v25, v8, v11
	v_max_f32_e32 v18, v12, v10
	v_min_f32_e32 v19, v12, v10
	s_waitcnt vmcnt(3)
	v_mfma_f32_32x32x16_bf16 v[2:17], v[2:5], v[46:49], 0
	s_waitcnt vmcnt(2)
	v_mfma_f32_32x32x16_bf16 v[2:17], v[58:61], v[42:45], v[2:17]
	s_waitcnt vmcnt(1)
	v_mfma_f32_32x32x16_bf16 v[2:17], v[54:57], v[38:41], v[2:17]
	s_waitcnt vmcnt(0)
	v_mfma_f32_32x32x16_bf16 v[2:17], v[50:53], v[34:37], v[2:17]
	s_nop 11
	v_and_or_b32 v2, v2, s33, v120
	v_and_or_b32 v3, v3, s33, v122
	v_and_or_b32 v4, v4, s33, v123
	v_and_or_b32 v5, v5, s33, v124
	v_and_or_b32 v6, v6, s33, v125
	v_and_or_b32 v7, v7, s33, v126
	v_and_or_b32 v8, v8, s33, v127
	v_and_or_b32 v9, v9, s33, v128
	v_and_or_b32 v10, v10, s33, v129
	v_and_or_b32 v11, v11, s33, v136
	v_and_or_b32 v12, v12, s33, v137
	v_and_or_b32 v13, v13, s33, v138
	v_and_or_b32 v14, v14, s33, v139
	v_and_or_b32 v15, v15, s33, v140
	v_and_or_b32 v16, v16, s33, v141
	v_and_or_b32 v17, v17, s33, v142
	v_max_f32_e32 v239, v2, v15
	v_min_f32_e32 v15, v2, v15
	v_max_f32_e32 v240, v3, v14
	v_min_f32_e32 v14, v3, v14
	v_max_f32_e32 v241, v4, v17
	v_min_f32_e32 v17, v4, v17
	v_max_f32_e32 v242, v5, v16
	v_min_f32_e32 v16, v5, v16
	v_max_f32_e32 v243, v6, v10
	v_min_f32_e32 v10, v6, v10
	v_max_f32_e32 v244, v7, v8
	v_min_f32_e32 v8, v7, v8
	v_max_f32_e32 v245, v9, v13
	v_min_f32_e32 v13, v9, v13
	v_max_f32_e32 v246, v11, v12
	v_min_f32_e32 v12, v11, v12
	v_max_f32_e32 v2, v239, v244
	v_min_f32_e32 v244, v239, v244
	v_max_f32_e32 v239, v240, v245
	v_min_f32_e32 v245, v240, v245
	v_max_f32_e32 v240, v241, v246
	v_min_f32_e32 v246, v241, v246
	v_max_f32_e32 v241, v242, v243
	v_min_f32_e32 v243, v242, v243
	v_max_f32_e32 v242, v8, v15
	v_min_f32_e32 v15, v8, v15
	v_max_f32_e32 v3, v10, v16
	v_min_f32_e32 v16, v10, v16
	v_max_f32_e32 v4, v12, v17
	v_min_f32_e32 v17, v12, v17
	v_max_f32_e32 v5, v13, v14
	v_min_f32_e32 v14, v13, v14
	v_max_f32_e32 v6, v2, v239
	v_min_f32_e32 v239, v2, v239
	v_max_f32_e32 v2, v240, v241
	v_min_f32_e32 v241, v240, v241
	v_max_f32_e32 v240, v243, v244
	v_min_f32_e32 v244, v243, v244
	v_max_f32_e32 v243, v242, v3
	v_min_f32_e32 v3, v242, v3
	v_max_f32_e32 v242, v245, v246
	v_min_f32_e32 v246, v245, v246
	v_max_f32_e32 v245, v4, v5
	v_min_f32_e32 v5, v4, v5
	v_max_f32_e32 v4, v14, v15
	v_min_f32_e32 v15, v14, v15
	v_max_f32_e32 v7, v16, v17
	v_min_f32_e32 v17, v16, v17
	v_max_f32_e32 v154, v6, v2
	v_min_f32_e32 v2, v6, v2
	v_max_f32_e32 v6, v239, v241
	v_min_f32_e32 v241, v239, v241
	v_max_f32_e32 v239, v240, v245
	v_min_f32_e32 v245, v240, v245
	v_max_f32_e32 v240, v244, v5
	v_min_f32_e32 v5, v244, v5
	v_max_f32_e32 v244, v243, v242
	v_min_f32_e32 v242, v243, v242
	v_max_f32_e32 v243, v3, v246
	v_min_f32_e32 v246, v3, v246
	v_max_f32_e32 v3, v4, v7
	v_min_f32_e32 v7, v4, v7
	v_min_f32_e32 v238, v15, v17
	v_max_f32_e32 v15, v15, v17
	v_max_f32_e32 v4, v6, v2
	v_min_f32_e32 v2, v6, v2
	v_max_f32_e32 v6, v241, v3
	v_min_f32_e32 v3, v241, v3
	v_max_f32_e32 v241, v239, v244
	v_min_f32_e32 v244, v239, v244
	v_max_f32_e32 v239, v240, v242
	v_min_f32_e32 v242, v240, v242
	v_max_f32_e32 v240, v243, v245
	v_min_f32_e32 v245, v243, v245
	v_max_f32_e32 v243, v246, v5
	v_min_f32_e32 v5, v246, v5
	v_max_f32_e32 v246, v15, v7
	v_min_f32_e32 v7, v15, v7
	v_max_f32_e32 v205, v4, v241
	v_min_f32_e32 v241, v4, v241
	v_max_f32_e32 v4, v2, v244
	v_min_f32_e32 v244, v2, v244
	v_max_f32_e32 v2, v239, v240
	v_min_f32_e32 v240, v239, v240
	v_max_f32_e32 v239, v242, v245
	v_min_f32_e32 v245, v242, v245
	v_max_f32_e32 v242, v243, v246
	v_min_f32_e32 v246, v243, v246
	v_min_f32_e32 v237, v5, v7
	v_max_f32_e32 v5, v5, v7
	v_max_f32_e32 v206, v4, v241
	v_min_f32_e32 v241, v4, v241
	v_max_f32_e32 v243, v6, v244
	v_min_f32_e32 v244, v6, v244
	v_max_f32_e32 v4, v242, v3
	v_min_f32_e32 v3, v242, v3
	v_min_f32_e32 v236, v5, v246
	v_max_f32_e32 v5, v5, v246
	v_max_f32_e32 v242, v243, v2
	v_min_f32_e32 v2, v243, v2
	v_max_f32_e32 v243, v244, v240
	v_min_f32_e32 v240, v244, v240
	v_max_f32_e32 v244, v239, v4
	v_min_f32_e32 v4, v239, v4
	v_max_f32_e32 v239, v245, v3
	v_min_f32_e32 v3, v245, v3
	v_max_f32_e32 v207, v242, v241
	v_min_f32_e32 v227, v242, v241
	v_max_f32_e32 v228, v2, v243
	v_min_f32_e32 v243, v2, v243
	v_max_f32_e32 v241, v244, v240
	v_min_f32_e32 v240, v244, v240
	v_min_f32_e32 v233, v4, v239
	v_max_f32_e32 v4, v4, v239
	v_max_f32_e32 v234, v5, v3
	v_min_f32_e32 v235, v5, v3
	v_max_f32_e32 v229, v243, v241
	v_min_f32_e32 v230, v243, v241
	v_max_f32_e32 v231, v240, v4
	v_min_f32_e32 v232, v240, v4
	global_load_dwordx4 v[50:53], v[92:93], off offset:96
	global_load_dwordx4 v[54:57], v[92:93], off offset:64
	global_load_dwordx4 v[58:61], v[92:93], off offset:32
	global_load_dwordx4 v[2:5], v[92:93], off
	s_waitcnt vmcnt(0)
	v_mfma_f32_32x32x16_bf16 v[2:17], v[2:5], v[46:49], 0
	v_mfma_f32_32x32x16_bf16 v[2:17], v[58:61], v[42:45], v[2:17]
	v_mfma_f32_32x32x16_bf16 v[2:17], v[54:57], v[38:41], v[2:17]
	v_mfma_f32_32x32x16_bf16 v[2:17], v[50:53], v[34:37], v[2:17]
	s_nop 11
	v_and_or_b32 v2, v2, s33, v143
	v_and_or_b32 v3, v3, s33, v144
	v_and_or_b32 v4, v4, s33, v145
	v_and_or_b32 v5, v5, s33, v146
	v_and_or_b32 v6, v6, s33, v147
	v_and_or_b32 v7, v7, s33, v148
	v_and_or_b32 v8, v8, s33, v149
	v_and_or_b32 v9, v9, s33, v150
	v_and_or_b32 v10, v10, s33, v151
	v_and_or_b32 v11, v11, s33, v152
	v_and_or_b32 v12, v12, s33, v153
	v_and_or_b32 v13, v13, s33, v160
	v_and_or_b32 v14, v14, s33, v161
	v_and_or_b32 v15, v15, s33, v162
	v_and_or_b32 v16, v16, s33, v163
	v_and_or_b32 v17, v17, s33, v164
	v_max_f32_e32 v239, v2, v15
	v_min_f32_e32 v15, v2, v15
	v_max_f32_e32 v2, v3, v14
	v_min_f32_e32 v14, v3, v14
	v_max_f32_e32 v3, v4, v17
	v_min_f32_e32 v17, v4, v17
	v_max_f32_e32 v4, v5, v16
	v_min_f32_e32 v16, v5, v16
	v_max_f32_e32 v5, v6, v10
	v_min_f32_e32 v10, v6, v10
	v_max_f32_e32 v6, v7, v8
	v_min_f32_e32 v8, v7, v8
	v_max_f32_e32 v7, v9, v13
	v_min_f32_e32 v13, v9, v13
	v_max_f32_e32 v9, v11, v12
	v_min_f32_e32 v12, v11, v12
	v_max_f32_e32 v11, v239, v6
	v_min_f32_e32 v6, v239, v6
	v_max_f32_e32 v239, v2, v7
	v_min_f32_e32 v7, v2, v7
	v_max_f32_e32 v2, v3, v9
	v_min_f32_e32 v9, v3, v9
	v_max_f32_e32 v3, v4, v5
	v_min_f32_e32 v5, v4, v5
	v_max_f32_e32 v4, v8, v15
	v_min_f32_e32 v15, v8, v15
	v_max_f32_e32 v8, v10, v16
	v_min_f32_e32 v16, v10, v16
	v_max_f32_e32 v10, v12, v17
	v_min_f32_e32 v17, v12, v17
	v_max_f32_e32 v12, v13, v14
	v_min_f32_e32 v14, v13, v14
	v_max_f32_e32 v13, v11, v239
	v_min_f32_e32 v239, v11, v239
	v_max_f32_e32 v11, v2, v3
	v_min_f32_e32 v3, v2, v3
	v_max_f32_e32 v2, v5, v6
	v_min_f32_e32 v6, v5, v6
	v_max_f32_e32 v5, v4, v8
	v_min_f32_e32 v8, v4, v8
	v_max_f32_e32 v4, v7, v9
	v_min_f32_e32 v9, v7, v9
	v_max_f32_e32 v7, v10, v12
	v_min_f32_e32 v12, v10, v12
	v_max_f32_e32 v10, v14, v15
	v_min_f32_e32 v15, v14, v15
	v_max_f32_e32 v14, v16, v17
	v_min_f32_e32 v17, v16, v17
	v_max_f32_e32 v16, v13, v11
	v_min_f32_e32 v11, v13, v11
	v_max_f32_e32 v13, v239, v3
	v_min_f32_e32 v3, v239, v3
	v_max_f32_e32 v239, v2, v7
	v_min_f32_e32 v7, v2, v7
	v_max_f32_e32 v2, v6, v12
	v_min_f32_e32 v12, v6, v12
	v_max_f32_e32 v6, v5, v4
	v_min_f32_e32 v4, v5, v4
	v_max_f32_e32 v5, v8, v9
	v_min_f32_e32 v9, v8, v9
	v_max_f32_e32 v8, v10, v14
	v_min_f32_e32 v14, v10, v14
	v_max_f32_e32 v10, v15, v17
	v_min_f32_e32 v17, v15, v17
	v_max_f32_e32 v15, v13, v11
	v_min_f32_e32 v11, v13, v11
	v_max_f32_e32 v13, v3, v8
	v_min_f32_e32 v8, v3, v8
	v_max_f32_e32 v3, v239, v6
	v_min_f32_e32 v6, v239, v6
	v_max_f32_e32 v239, v2, v4
	v_min_f32_e32 v4, v2, v4
	v_max_f32_e32 v2, v5, v7
	v_min_f32_e32 v7, v5, v7
	v_max_f32_e32 v5, v9, v12
	v_min_f32_e32 v12, v9, v12
	v_max_f32_e32 v9, v10, v14
	v_min_f32_e32 v14, v10, v14
	v_max_f32_e32 v10, v15, v3
	v_min_f32_e32 v3, v15, v3
	v_max_f32_e32 v15, v11, v6
	v_min_f32_e32 v6, v11, v6
	v_max_f32_e32 v11, v239, v2
	v_min_f32_e32 v2, v239, v2
	v_max_f32_e32 v239, v4, v7
	v_min_f32_e32 v7, v4, v7
	v_max_f32_e32 v4, v5, v9
	v_min_f32_e32 v9, v5, v9
	v_max_f32_e32 v5, v12, v14
	v_min_f32_e32 v14, v12, v14
	v_max_f32_e32 v12, v15, v3
	v_min_f32_e32 v3, v15, v3
	v_max_f32_e32 v15, v13, v6
	v_min_f32_e32 v6, v13, v6
	v_max_f32_e32 v13, v4, v8
	v_min_f32_e32 v8, v4, v8
	v_max_f32_e32 v4, v5, v9
	v_min_f32_e32 v9, v5, v9
	v_max_f32_e32 v5, v15, v11
	v_min_f32_e32 v11, v15, v11
	v_max_f32_e32 v15, v6, v2
	v_min_f32_e32 v2, v6, v2
	v_max_f32_e32 v6, v239, v13
	v_min_f32_e32 v13, v239, v13
	v_max_f32_e32 v239, v7, v8
	v_min_f32_e32 v8, v7, v8
	v_max_f32_e32 v7, v5, v3
	v_min_f32_e32 v3, v5, v3
	v_max_f32_e32 v5, v11, v15
	v_min_f32_e32 v15, v11, v15
	v_max_f32_e32 v11, v6, v2
	v_min_f32_e32 v2, v6, v2
	v_max_f32_e32 v6, v13, v239
	v_min_f32_e32 v239, v13, v239
	v_max_f32_e32 v13, v4, v8
	v_min_f32_e32 v8, v4, v8
	v_max_f32_e32 v4, v15, v11
	v_min_f32_e32 v11, v15, v11
	v_max_f32_e32 v15, v2, v6
	v_min_f32_e32 v6, v2, v6
	v_max_f32_e32 v17, v154, v17
	v_max_f32_e32 v14, v205, v14
	v_max_f32_e32 v9, v206, v9
	v_max_f32_e32 v8, v207, v8
	v_max_f32_e32 v13, v227, v13
	v_max_f32_e32 v239, v228, v239
	v_max_f32_e32 v6, v229, v6
	v_max_f32_e32 v15, v230, v15
	v_max_f32_e32 v11, v231, v11
	v_max_f32_e32 v4, v232, v4
	v_max_f32_e32 v5, v233, v5
	v_max_f32_e32 v3, v234, v3
	v_max_f32_e32 v7, v235, v7
	v_max_f32_e32 v12, v236, v12
	v_max_f32_e32 v10, v237, v10
	v_max_f32_e32 v16, v238, v16
	v_max_f32_e32 v2, v16, v15
	v_min_f32_e32 v15, v16, v15
	v_max_f32_e32 v16, v10, v6
	v_min_f32_e32 v6, v10, v6
	v_max_f32_e32 v10, v12, v239
	v_min_f32_e32 v239, v12, v239
	v_max_f32_e32 v12, v7, v13
	v_min_f32_e32 v13, v7, v13
	v_max_f32_e32 v7, v3, v8
	v_min_f32_e32 v8, v3, v8
	v_max_f32_e32 v3, v5, v9
	v_min_f32_e32 v9, v5, v9
	v_max_f32_e32 v5, v4, v14
	v_min_f32_e32 v14, v4, v14
	v_max_f32_e32 v4, v11, v17
	v_min_f32_e32 v17, v11, v17
	v_max_f32_e32 v11, v2, v7
	v_min_f32_e32 v7, v2, v7
	v_max_f32_e32 v2, v16, v3
	v_min_f32_e32 v3, v16, v3
	v_max_f32_e32 v16, v10, v5
	v_min_f32_e32 v5, v10, v5
	v_max_f32_e32 v10, v12, v4
	v_min_f32_e32 v4, v12, v4
	v_max_f32_e32 v12, v15, v8
	v_min_f32_e32 v8, v15, v8
	v_max_f32_e32 v15, v6, v9
	v_min_f32_e32 v9, v6, v9
	v_max_f32_e32 v6, v239, v14
	v_min_f32_e32 v14, v239, v14
	v_max_f32_e32 v154, v13, v17
	v_min_f32_e32 v17, v13, v17
	v_max_f32_e32 v13, v11, v16
	v_min_f32_e32 v16, v11, v16
	v_max_f32_e32 v11, v2, v10
	v_min_f32_e32 v10, v2, v10
	v_max_f32_e32 v2, v7, v5
	v_min_f32_e32 v5, v7, v5
	v_max_f32_e32 v7, v3, v4
	v_min_f32_e32 v4, v3, v4
	v_max_f32_e32 v3, v12, v6
	v_min_f32_e32 v6, v12, v6
	v_max_f32_e32 v12, v15, v154
	v_min_f32_e32 v154, v15, v154
	v_max_f32_e32 v15, v8, v14
	v_min_f32_e32 v14, v8, v14
	v_max_f32_e32 v8, v9, v17
	v_min_f32_e32 v17, v9, v17
	v_max_f32_e32 v239, v13, v11
	v_min_f32_e32 v240, v13, v11
	v_max_f32_e32 v241, v16, v10
	v_min_f32_e32 v242, v16, v10
	v_max_f32_e32 v243, v2, v7
	v_min_f32_e32 v244, v2, v7
	v_max_f32_e32 v245, v5, v4
	v_min_f32_e32 v246, v5, v4
	v_max_f32_e32 v247, v3, v12
	v_min_f32_e32 v252, v3, v12
	v_max_f32_e32 v253, v6, v154
	v_min_f32_e32 v154, v6, v154
	v_max_f32_e32 v205, v15, v8
	v_min_f32_e32 v206, v15, v8
	v_max_f32_e32 v207, v14, v17
	v_min_f32_e32 v227, v14, v17
	global_load_dwordx4 v[50:53], v[94:95], off offset:96
	global_load_dwordx4 v[54:57], v[94:95], off offset:64
	global_load_dwordx4 v[58:61], v[94:95], off offset:32
	global_load_dwordx4 v[2:5], v[94:95], off
	s_waitcnt vmcnt(0)
	v_mfma_f32_32x32x16_bf16 v[2:17], v[2:5], v[46:49], 0
	v_mfma_f32_32x32x16_bf16 v[2:17], v[58:61], v[42:45], v[2:17]
	v_mfma_f32_32x32x16_bf16 v[2:17], v[54:57], v[38:41], v[2:17]
	v_mfma_f32_32x32x16_bf16 v[2:17], v[50:53], v[34:37], v[2:17]
	s_nop 11
	v_and_or_b32 v2, v2, s33, v165
	v_and_or_b32 v3, v3, s33, v166
	v_and_or_b32 v4, v4, s33, v167
	v_and_or_b32 v5, v5, s33, v168
	v_and_or_b32 v6, v6, s33, v169
	v_and_or_b32 v7, v7, s33, v170
	v_and_or_b32 v8, v8, s33, v171
	v_and_or_b32 v9, v9, s33, v172
	v_and_or_b32 v10, v10, s33, v173
	v_and_or_b32 v11, v11, s33, v174
	v_and_or_b32 v12, v12, s33, v175
	v_and_or_b32 v13, v13, s33, v184
	v_and_or_b32 v14, v14, s33, v185
	v_and_or_b32 v15, v15, s33, v186
	v_and_or_b32 v16, v16, s33, v187
	v_and_or_b32 v17, v17, s33, v188
	v_max_f32_e32 v228, v2, v15
	v_min_f32_e32 v15, v2, v15
	v_max_f32_e32 v2, v3, v14
	v_min_f32_e32 v14, v3, v14
	v_max_f32_e32 v3, v4, v17
	v_min_f32_e32 v17, v4, v17
	v_max_f32_e32 v4, v5, v16
	v_min_f32_e32 v16, v5, v16
	v_max_f32_e32 v5, v6, v10
	v_min_f32_e32 v10, v6, v10
	v_max_f32_e32 v6, v7, v8
	v_min_f32_e32 v8, v7, v8
	v_max_f32_e32 v7, v9, v13
	v_min_f32_e32 v13, v9, v13
	v_max_f32_e32 v9, v11, v12
	v_min_f32_e32 v12, v11, v12
	v_max_f32_e32 v11, v228, v6
	v_min_f32_e32 v6, v228, v6
	v_max_f32_e32 v228, v2, v7
	v_min_f32_e32 v7, v2, v7
	v_max_f32_e32 v2, v3, v9
	v_min_f32_e32 v9, v3, v9
	v_max_f32_e32 v3, v4, v5
	v_min_f32_e32 v5, v4, v5
	v_max_f32_e32 v4, v8, v15
	v_min_f32_e32 v15, v8, v15
	v_max_f32_e32 v8, v10, v16
	v_min_f32_e32 v16, v10, v16
	v_max_f32_e32 v10, v12, v17
	v_min_f32_e32 v17, v12, v17
	v_max_f32_e32 v12, v13, v14
	v_min_f32_e32 v14, v13, v14
	v_max_f32_e32 v13, v11, v228
	v_min_f32_e32 v228, v11, v228
	v_max_f32_e32 v11, v2, v3
	v_min_f32_e32 v3, v2, v3
	v_max_f32_e32 v2, v5, v6
	v_min_f32_e32 v6, v5, v6
	v_max_f32_e32 v5, v4, v8
	v_min_f32_e32 v8, v4, v8
	v_max_f32_e32 v4, v7, v9
	v_min_f32_e32 v9, v7, v9
	v_max_f32_e32 v7, v10, v12
	v_min_f32_e32 v12, v10, v12
	v_max_f32_e32 v10, v14, v15
	v_min_f32_e32 v15, v14, v15
	v_max_f32_e32 v14, v16, v17
	v_min_f32_e32 v17, v16, v17
	v_max_f32_e32 v16, v13, v11
	v_min_f32_e32 v11, v13, v11
	v_max_f32_e32 v13, v228, v3
	v_min_f32_e32 v3, v228, v3
	v_max_f32_e32 v228, v2, v7
	v_min_f32_e32 v7, v2, v7
	v_max_f32_e32 v2, v6, v12
	v_min_f32_e32 v12, v6, v12
	v_max_f32_e32 v6, v5, v4
	v_min_f32_e32 v4, v5, v4
	v_max_f32_e32 v5, v8, v9
	v_min_f32_e32 v9, v8, v9
	v_max_f32_e32 v8, v10, v14
	v_min_f32_e32 v14, v10, v14
	v_max_f32_e32 v10, v15, v17
	v_min_f32_e32 v17, v15, v17
	v_max_f32_e32 v15, v13, v11
	v_min_f32_e32 v11, v13, v11
	v_max_f32_e32 v13, v3, v8
	v_min_f32_e32 v8, v3, v8
	v_max_f32_e32 v3, v228, v6
	v_min_f32_e32 v6, v228, v6
	v_max_f32_e32 v228, v2, v4
	v_min_f32_e32 v4, v2, v4
	v_max_f32_e32 v2, v5, v7
	v_min_f32_e32 v7, v5, v7
	v_max_f32_e32 v5, v9, v12
	v_min_f32_e32 v12, v9, v12
	v_max_f32_e32 v9, v10, v14
	v_min_f32_e32 v14, v10, v14
	v_max_f32_e32 v10, v15, v3
	v_min_f32_e32 v3, v15, v3
	v_max_f32_e32 v15, v11, v6
	v_min_f32_e32 v6, v11, v6
	v_max_f32_e32 v11, v228, v2
	v_min_f32_e32 v2, v228, v2
	v_max_f32_e32 v228, v4, v7
	v_min_f32_e32 v7, v4, v7
	v_max_f32_e32 v4, v5, v9
	v_min_f32_e32 v9, v5, v9
	v_max_f32_e32 v5, v12, v14
	v_min_f32_e32 v14, v12, v14
	v_max_f32_e32 v12, v15, v3
	v_min_f32_e32 v3, v15, v3
	v_max_f32_e32 v15, v13, v6
	v_min_f32_e32 v6, v13, v6
	v_max_f32_e32 v13, v4, v8
	v_min_f32_e32 v8, v4, v8
	v_max_f32_e32 v4, v5, v9
	v_min_f32_e32 v9, v5, v9
	v_max_f32_e32 v5, v15, v11
	v_min_f32_e32 v11, v15, v11
	v_max_f32_e32 v15, v6, v2
	v_min_f32_e32 v2, v6, v2
	v_max_f32_e32 v6, v228, v13
	v_min_f32_e32 v13, v228, v13
	v_max_f32_e32 v228, v7, v8
	v_min_f32_e32 v8, v7, v8
	v_max_f32_e32 v7, v5, v3
	v_min_f32_e32 v3, v5, v3
	v_max_f32_e32 v5, v11, v15
	v_min_f32_e32 v15, v11, v15
	v_max_f32_e32 v11, v6, v2
	v_min_f32_e32 v2, v6, v2
	v_max_f32_e32 v6, v13, v228
	v_min_f32_e32 v228, v13, v228
	v_max_f32_e32 v13, v4, v8
	v_min_f32_e32 v8, v4, v8
	v_max_f32_e32 v4, v15, v11
	v_min_f32_e32 v11, v15, v11
	v_max_f32_e32 v15, v2, v6
	v_min_f32_e32 v6, v2, v6
	v_max_f32_e32 v17, v239, v17
	v_max_f32_e32 v14, v240, v14
	v_max_f32_e32 v9, v241, v9
	v_max_f32_e32 v8, v242, v8
	v_max_f32_e32 v13, v243, v13
	v_max_f32_e32 v228, v244, v228
	v_max_f32_e32 v6, v245, v6
	v_max_f32_e32 v15, v246, v15
	v_max_f32_e32 v11, v247, v11
	v_max_f32_e32 v4, v252, v4
	v_max_f32_e32 v5, v253, v5
	v_max_f32_e32 v3, v154, v3
	v_max_f32_e32 v7, v205, v7
	v_max_f32_e32 v12, v206, v12
	v_max_f32_e32 v10, v207, v10
	v_max_f32_e32 v16, v227, v16
	v_max_f32_e32 v2, v16, v15
	v_min_f32_e32 v15, v16, v15
	v_max_f32_e32 v16, v10, v6
	v_min_f32_e32 v6, v10, v6
	v_max_f32_e32 v10, v12, v228
	v_min_f32_e32 v228, v12, v228
	v_max_f32_e32 v12, v7, v13
	v_min_f32_e32 v13, v7, v13
	v_max_f32_e32 v7, v3, v8
	v_min_f32_e32 v8, v3, v8
	v_max_f32_e32 v3, v5, v9
	v_min_f32_e32 v9, v5, v9
	v_max_f32_e32 v5, v4, v14
	v_min_f32_e32 v14, v4, v14
	v_max_f32_e32 v4, v11, v17
	v_min_f32_e32 v17, v11, v17
	v_max_f32_e32 v11, v2, v7
	v_min_f32_e32 v7, v2, v7
	v_max_f32_e32 v2, v16, v3
	v_min_f32_e32 v3, v16, v3
	v_max_f32_e32 v16, v10, v5
	v_min_f32_e32 v5, v10, v5
	v_max_f32_e32 v10, v12, v4
	v_min_f32_e32 v4, v12, v4
	v_max_f32_e32 v12, v15, v8
	v_min_f32_e32 v8, v15, v8
	v_max_f32_e32 v15, v6, v9
	v_min_f32_e32 v9, v6, v9
	v_max_f32_e32 v6, v228, v14
	v_min_f32_e32 v14, v228, v14
	v_max_f32_e32 v239, v13, v17
	v_min_f32_e32 v17, v13, v17
	v_max_f32_e32 v13, v11, v16
	v_min_f32_e32 v16, v11, v16
	v_max_f32_e32 v11, v2, v10
	v_min_f32_e32 v10, v2, v10
	v_max_f32_e32 v2, v7, v5
	v_min_f32_e32 v5, v7, v5
	v_max_f32_e32 v7, v3, v4
	v_min_f32_e32 v4, v3, v4
	v_max_f32_e32 v3, v12, v6
	v_min_f32_e32 v6, v12, v6
	v_max_f32_e32 v12, v15, v239
	v_min_f32_e32 v239, v15, v239
	v_max_f32_e32 v15, v8, v14
	v_min_f32_e32 v14, v8, v14
	v_max_f32_e32 v8, v9, v17
	v_min_f32_e32 v17, v9, v17
	v_max_f32_e32 v228, v13, v11
	v_min_f32_e32 v229, v13, v11
	v_max_f32_e32 v230, v16, v10
	v_min_f32_e32 v231, v16, v10
	v_max_f32_e32 v232, v2, v7
	v_min_f32_e32 v233, v2, v7
	v_max_f32_e32 v234, v5, v4
	v_min_f32_e32 v235, v5, v4
	v_max_f32_e32 v236, v3, v12
	v_min_f32_e32 v237, v3, v12
	v_max_f32_e32 v238, v6, v239
	v_min_f32_e32 v154, v6, v239
	v_max_f32_e32 v205, v15, v8
	v_min_f32_e32 v206, v15, v8
	v_max_f32_e32 v207, v14, v17
	v_min_f32_e32 v227, v14, v17
	global_load_dwordx4 v[50:53], v[96:97], off offset:96
	global_load_dwordx4 v[54:57], v[96:97], off offset:64
	global_load_dwordx4 v[58:61], v[96:97], off offset:32
	global_load_dwordx4 v[2:5], v[96:97], off
	s_waitcnt vmcnt(0)
	v_mfma_f32_32x32x16_bf16 v[2:17], v[2:5], v[46:49], 0
	v_mfma_f32_32x32x16_bf16 v[2:17], v[58:61], v[42:45], v[2:17]
	v_mfma_f32_32x32x16_bf16 v[2:17], v[54:57], v[38:41], v[2:17]
	v_mfma_f32_32x32x16_bf16 v[2:17], v[50:53], v[34:37], v[2:17]
	s_nop 11
	v_and_or_b32 v2, v2, s33, v189
	v_and_or_b32 v3, v3, s33, v190
	v_and_or_b32 v4, v4, s33, v191
	v_and_or_b32 v5, v5, s33, v192
	v_and_or_b32 v6, v6, s33, v193
	v_and_or_b32 v7, v7, s33, v194
	v_and_or_b32 v8, v8, s33, v195
	v_and_or_b32 v9, v9, s33, v196
	v_and_or_b32 v10, v10, s33, v197
	v_and_or_b32 v11, v11, s33, v198
	v_and_or_b32 v12, v12, s33, v199
	v_and_or_b32 v13, v13, s33, v200
	v_and_or_b32 v14, v14, s33, v201
	v_and_or_b32 v15, v15, s33, v202
	v_and_or_b32 v16, v16, s33, v203
	v_and_or_b32 v17, v17, s33, v204
	v_max_f32_e32 v35, v2, v15
	v_min_f32_e32 v15, v2, v15
	v_max_f32_e32 v36, v3, v14
	v_min_f32_e32 v14, v3, v14
	v_max_f32_e32 v37, v4, v17
	v_min_f32_e32 v17, v4, v17
	v_max_f32_e32 v38, v5, v16
	v_min_f32_e32 v16, v5, v16
	v_max_f32_e32 v39, v6, v10
	v_min_f32_e32 v10, v6, v10
	v_max_f32_e32 v40, v7, v8
	v_min_f32_e32 v8, v7, v8
	v_max_f32_e32 v41, v9, v13
	v_min_f32_e32 v13, v9, v13
	v_max_f32_e32 v42, v11, v12
	v_min_f32_e32 v12, v11, v12
	v_max_f32_e32 v43, v35, v40
	v_min_f32_e32 v40, v35, v40
	v_max_f32_e32 v35, v36, v41
	v_min_f32_e32 v41, v36, v41
	v_max_f32_e32 v36, v37, v42
	v_min_f32_e32 v42, v37, v42
	v_max_f32_e32 v37, v38, v39
	v_min_f32_e32 v39, v38, v39
	v_max_f32_e32 v38, v8, v15
	v_min_f32_e32 v15, v8, v15
	v_max_f32_e32 v44, v10, v16
	v_min_f32_e32 v16, v10, v16
	v_max_f32_e32 v45, v12, v17
	v_min_f32_e32 v17, v12, v17
	v_max_f32_e32 v46, v13, v14
	v_min_f32_e32 v14, v13, v14
	v_max_f32_e32 v47, v43, v35
	v_min_f32_e32 v35, v43, v35
	v_max_f32_e32 v43, v36, v37
	v_min_f32_e32 v37, v36, v37
	v_max_f32_e32 v36, v39, v40
	v_min_f32_e32 v40, v39, v40
	v_max_f32_e32 v39, v38, v44
	v_min_f32_e32 v44, v38, v44
	v_max_f32_e32 v38, v41, v42
	v_min_f32_e32 v42, v41, v42
	v_max_f32_e32 v41, v45, v46
	v_min_f32_e32 v46, v45, v46
	v_max_f32_e32 v45, v14, v15
	v_min_f32_e32 v15, v14, v15
	v_max_f32_e32 v48, v16, v17
	v_min_f32_e32 v17, v16, v17
	v_max_f32_e32 v2, v47, v43
	v_min_f32_e32 v43, v47, v43
	v_max_f32_e32 v47, v35, v37
	v_min_f32_e32 v37, v35, v37
	v_max_f32_e32 v35, v36, v41
	v_min_f32_e32 v41, v36, v41
	v_max_f32_e32 v36, v40, v46
	v_min_f32_e32 v46, v40, v46
	v_max_f32_e32 v40, v39, v38
	v_min_f32_e32 v38, v39, v38
	v_max_f32_e32 v39, v44, v42
	v_min_f32_e32 v42, v44, v42
	v_max_f32_e32 v44, v45, v48
	v_min_f32_e32 v48, v45, v48
	v_max_f32_e32 v45, v15, v17
	v_min_f32_e32 v17, v15, v17
	v_max_f32_e32 v3, v47, v43
	v_min_f32_e32 v43, v47, v43
	v_max_f32_e32 v47, v37, v44
	v_min_f32_e32 v44, v37, v44
	v_max_f32_e32 v37, v35, v40
	v_min_f32_e32 v40, v35, v40
	v_max_f32_e32 v35, v36, v38
	v_min_f32_e32 v38, v36, v38
	v_max_f32_e32 v36, v39, v41
	v_min_f32_e32 v41, v39, v41
	v_max_f32_e32 v39, v42, v46
	v_min_f32_e32 v46, v42, v46
	v_max_f32_e32 v42, v45, v48
	v_min_f32_e32 v48, v45, v48
	v_max_f32_e32 v45, v3, v37
	v_min_f32_e32 v37, v3, v37
	v_max_f32_e32 v3, v43, v40
	v_min_f32_e32 v40, v43, v40
	v_max_f32_e32 v43, v35, v36
	v_min_f32_e32 v36, v35, v36
	v_max_f32_e32 v35, v38, v41
	v_min_f32_e32 v41, v38, v41
	v_max_f32_e32 v38, v39, v42
	v_min_f32_e32 v42, v39, v42
	v_max_f32_e32 v39, v46, v48
	v_min_f32_e32 v48, v46, v48
	v_max_f32_e32 v46, v3, v37
	v_min_f32_e32 v37, v3, v37
	v_max_f32_e32 v3, v47, v40
	v_min_f32_e32 v40, v47, v40
	v_max_f32_e32 v47, v38, v44
	v_min_f32_e32 v44, v38, v44
	v_max_f32_e32 v38, v39, v42
	v_min_f32_e32 v42, v39, v42
	v_max_f32_e32 v39, v3, v43
	v_min_f32_e32 v43, v3, v43
	v_max_f32_e32 v3, v40, v36
	v_min_f32_e32 v36, v40, v36
	v_max_f32_e32 v40, v35, v47
	v_min_f32_e32 v47, v35, v47
	v_max_f32_e32 v35, v41, v44
	v_min_f32_e32 v44, v41, v44
	v_max_f32_e32 v41, v39, v37
	v_min_f32_e32 v37, v39, v37
	v_max_f32_e32 v39, v43, v3
	v_min_f32_e32 v3, v43, v3
	v_max_f32_e32 v43, v40, v36
	v_min_f32_e32 v36, v40, v36
	v_max_f32_e32 v40, v47, v35
	v_min_f32_e32 v35, v47, v35
	v_max_f32_e32 v47, v38, v44
	v_min_f32_e32 v44, v38, v44
	v_max_f32_e32 v38, v3, v43
	v_min_f32_e32 v43, v3, v43
	v_max_f32_e32 v3, v36, v40
	v_min_f32_e32 v40, v36, v40
	v_max_f32_e32 v17, v228, v17
	v_max_f32_e32 v48, v229, v48
	v_max_f32_e32 v42, v230, v42
	v_max_f32_e32 v44, v231, v44
	v_max_f32_e32 v47, v232, v47
	v_max_f32_e32 v35, v233, v35
	v_max_f32_e32 v40, v234, v40
	v_max_f32_e32 v3, v235, v3
	v_max_f32_e32 v43, v236, v43
	v_max_f32_e32 v38, v237, v38
	v_max_f32_e32 v39, v238, v39
	v_max_f32_e32 v37, v154, v37
	v_max_f32_e32 v41, v205, v41
	v_max_f32_e32 v46, v206, v46
	v_max_f32_e32 v45, v207, v45
	v_max_f32_e32 v2, v227, v2
	v_max_f32_e32 v36, v2, v3
	v_min_f32_e32 v3, v2, v3
	v_max_f32_e32 v2, v45, v40
	v_min_f32_e32 v40, v45, v40
	v_max_f32_e32 v45, v46, v35
	v_min_f32_e32 v35, v46, v35
	v_max_f32_e32 v46, v41, v47
	v_min_f32_e32 v47, v41, v47
	v_max_f32_e32 v41, v37, v44
	v_min_f32_e32 v44, v37, v44
	v_max_f32_e32 v37, v39, v42
	v_min_f32_e32 v42, v39, v42
	v_max_f32_e32 v39, v38, v48
	v_min_f32_e32 v48, v38, v48
	v_max_f32_e32 v38, v43, v17
	v_min_f32_e32 v17, v43, v17
	v_max_f32_e32 v43, v36, v41
	v_min_f32_e32 v41, v36, v41
	v_max_f32_e32 v36, v2, v37
	v_min_f32_e32 v37, v2, v37
	v_max_f32_e32 v2, v45, v39
	v_min_f32_e32 v39, v45, v39
	v_max_f32_e32 v45, v46, v38
	v_min_f32_e32 v38, v46, v38
	v_max_f32_e32 v46, v3, v44
	v_min_f32_e32 v44, v3, v44
	v_max_f32_e32 v3, v40, v42
	v_min_f32_e32 v42, v40, v42
	v_max_f32_e32 v40, v35, v48
	v_min_f32_e32 v48, v35, v48
	v_max_f32_e32 v35, v47, v17
	v_min_f32_e32 v17, v47, v17
	v_max_f32_e32 v47, v43, v2
	v_min_f32_e32 v2, v43, v2
	v_max_f32_e32 v43, v36, v45
	v_min_f32_e32 v45, v36, v45
	v_max_f32_e32 v36, v41, v39
	v_min_f32_e32 v39, v41, v39
	v_max_f32_e32 v41, v37, v38
	v_min_f32_e32 v38, v37, v38
	v_max_f32_e32 v37, v46, v40
	v_min_f32_e32 v40, v46, v40
	v_max_f32_e32 v46, v3, v35
	v_min_f32_e32 v35, v3, v35
	v_max_f32_e32 v3, v44, v48
	v_min_f32_e32 v48, v44, v48
	v_max_f32_e32 v44, v42, v17
	v_min_f32_e32 v17, v42, v17
	v_max_f32_e32 v15, v47, v43
	v_min_f32_e32 v43, v47, v43
	v_max_f32_e32 v12, v2, v45
	v_min_f32_e32 v5, v2, v45
	v_max_f32_e32 v9, v36, v41
	v_min_f32_e32 v41, v36, v41
	v_max_f32_e32 v34, v39, v38
	v_min_f32_e32 v4, v39, v38
	v_max_f32_e32 v11, v37, v46
	v_min_f32_e32 v13, v37, v46
	v_max_f32_e32 v16, v40, v35
	v_min_f32_e32 v7, v40, v35
	v_max_f32_e32 v14, v3, v44
	v_min_f32_e32 v8, v3, v44
	v_max_f32_e32 v10, v48, v17
	v_min_f32_e32 v2, v48, v17
	v_mov_b32_e32 v3, v43
	v_mov_b32_e32 v17, v41
	ds_bpermute_b32 v6, v121, v15
	ds_bpermute_b32 v35, v121, v3
	ds_bpermute_b32 v36, v121, v12
	ds_bpermute_b32 v37, v121, v5
	ds_bpermute_b32 v38, v121, v9
	ds_bpermute_b32 v39, v121, v17
	ds_bpermute_b32 v40, v121, v34
	ds_bpermute_b32 v41, v121, v4
	ds_bpermute_b32 v42, v121, v11
	ds_bpermute_b32 v43, v121, v13
	ds_bpermute_b32 v44, v121, v16
	ds_bpermute_b32 v45, v121, v7
	ds_bpermute_b32 v46, v121, v14
	ds_bpermute_b32 v47, v121, v8
	ds_bpermute_b32 v48, v121, v10
	ds_bpermute_b32 v49, v121, v2
	s_waitcnt lgkmcnt(4)
	s_waitcnt lgkmcnt(3)
	s_waitcnt lgkmcnt(2)
	s_waitcnt lgkmcnt(1)
	s_waitcnt lgkmcnt(0)
	v_max_f32_e32 v15, v15, v49
	v_max_f32_e32 v3, v3, v48
	v_max_f32_e32 v12, v12, v47
	v_max_f32_e32 v5, v5, v46
	v_max_f32_e32 v9, v9, v45
	v_max_f32_e32 v17, v17, v44
	v_max_f32_e32 v34, v34, v43
	v_max_f32_e32 v4, v4, v42
	v_max_f32_e32 v11, v11, v41
	v_max_f32_e32 v13, v13, v40
	v_max_f32_e32 v16, v16, v39
	v_max_f32_e32 v7, v7, v38
	v_max_f32_e32 v14, v14, v37
	v_max_f32_e32 v8, v8, v36
	v_max_f32_e32 v10, v10, v35
	v_max_f32_e32 v2, v2, v6
	v_max_f32_e32 v6, v15, v11
	v_min_f32_e32 v11, v15, v11
	v_max_f32_e32 v15, v3, v13
	v_min_f32_e32 v3, v3, v13
	v_max_f32_e32 v13, v12, v16
	v_min_f32_e32 v12, v12, v16
	v_max_f32_e32 v16, v5, v7
	v_min_f32_e32 v5, v5, v7
	v_max_f32_e32 v7, v9, v14
	v_min_f32_e32 v9, v9, v14
	v_max_f32_e32 v14, v17, v8
	v_min_f32_e32 v8, v17, v8
	v_max_f32_e32 v17, v34, v10
	v_min_f32_e32 v10, v34, v10
	v_max_f32_e32 v34, v4, v2
	v_min_f32_e32 v2, v4, v2
	v_max_f32_e32 v4, v6, v7
	v_min_f32_e32 v6, v6, v7
	v_max_f32_e32 v7, v15, v14
	v_min_f32_e32 v14, v15, v14
	v_max_f32_e32 v15, v13, v17
	v_min_f32_e32 v13, v13, v17
	v_max_f32_e32 v17, v16, v34
	v_min_f32_e32 v16, v16, v34
	v_max_f32_e32 v34, v11, v9
	v_min_f32_e32 v9, v11, v9
	v_max_f32_e32 v11, v3, v8
	v_min_f32_e32 v3, v3, v8
	v_max_f32_e32 v8, v12, v10
	v_min_f32_e32 v10, v12, v10
	v_max_f32_e32 v12, v5, v2
	v_max_f32_e32 v36, v34, v8
	v_min_f32_e32 v8, v34, v8
	v_max_f32_e32 v34, v11, v12
	v_min_f32_e32 v37, v11, v12
	v_max_f32_e32 v38, v9, v10
	v_min_f32_e32 v9, v9, v10
	v_max_f32_e32 v10, v36, v34
	v_min_f32_e32 v11, v36, v34
	v_mov_b32_e32 v34, v119
	v_min_f32_e32 v2, v5, v2
	v_max_f32_e32 v5, v4, v15
	v_min_f32_e32 v15, v4, v15
	v_max_f32_e32 v4, v7, v17
	v_min_f32_e32 v7, v7, v17
	v_max_f32_e32 v17, v6, v13
	v_min_f32_e32 v6, v6, v13
	v_max_f32_e32 v13, v14, v16
	v_min_f32_e32 v35, v14, v16
	v_max_f32_e32 v39, v3, v2
	v_min_f32_e32 v40, v3, v2
	v_and_b32_e32 v34, 31, v34
	v_max_f32_e32 v2, v5, v4
	v_min_f32_e32 v3, v5, v4
	v_max_f32_e32 v4, v15, v7
	v_min_f32_e32 v5, v15, v7
	v_max_f32_e32 v14, v17, v13
	v_min_f32_e32 v15, v17, v13
	v_max_f32_e32 v16, v6, v35
	v_min_f32_e32 v17, v6, v35
	v_max_f32_e32 v12, v8, v37
	v_min_f32_e32 v13, v8, v37
	v_max_f32_e32 v6, v38, v39
	v_min_f32_e32 v7, v38, v39
	v_max_f32_e32 v8, v9, v40
	v_min_f32_e32 v9, v9, v40
	v_lshl_add_u32 v36, v34, 7, s43
	s_lshl_b32 s10, s44, 10
	v_add_u32_e32 v36, s10, v36
	s_and_saveexec_b64 s[40:41], s[12:13]
	s_cbranch_execz .LBB0_24
	ds_write_b128 v36, v[30:33]
	ds_write_b128 v36, v[2:5] offset:64
	ds_write_b128 v36, v[26:29] offset:16
	ds_write_b128 v36, v[14:17] offset:80
	ds_write_b128 v36, v[22:25] offset:32
	ds_write_b128 v36, v[10:13] offset:96
	ds_write_b128 v36, v[18:21] offset:48
	ds_write_b128 v36, v[6:9] offset:112
